# attention steady loop: -mhat carried in a 16-VGPR SrcC tuple (parked regs in idle O-stage LDS), removes 32 v_sub per KV tile
# speedup vs baseline: 1.0112x; 1.0112x over previous
; #define WAIT_BAR(N) asm volatile("s_waitcnt vmcnt(" #N ") lgkmcnt(0)\n\ts_barrier":::"memory")
;   #define DMA_K(t,slot) glds16(ksrc+(long)(t)*KVBLK*DM,(unsigned)__builtin_amdgcn_readfirstlane(kdst+(slot)))
;   #define DMA_V(t,slot) do{ glds16(vsrc+(long)(t)*KVBLK*DM,(unsigned)__builtin_amdgcn_readfirstlane(vdst+(slot))); glds16(vsrc+64+(long)(t)*KVBLK*DM,(unsigned)__builtin_amdgcn_readfirstlane(vdst2+(slot))); }while(0)
;   #define CMASK(P0,P1,t) do{int jb_=(t)-(NT-4); if(jb_>=0)cmask(P0,P1,jb_,qrel,hi);}while(0)
;   #define START(P0,P1) do{ resc=false; \
;     { _Pragma("unroll") for(int r=0;r<16;++r){P0[r]=fsub_s(P0[r],mhat);P1[r]=fsub_s(P1[r],mhat);} \
;       } \
;     _Pragma("unroll") for(int r=0;r<16;++r)P0[r]=__builtin_amdgcn_exp2f(P0[r]); }while(0)
;   #define ROT() do{sl_prev=sl_cur;sl_cur=sl_next;sl_next=(sl_next==(NSLOT-1)*SLOTB)?0:sl_next+SLOTB;}while(0)
;   #define CMASK(P0,P1,t) do{}while(0)
;   #define CMASK(P0,P1,t) do{int jb_=(t)-(NT-4); if(jb_>=0)cmask(P0,P1,jb_,qrel,hi);}while(0)
; template<int THRL> __device__ __forceinline__ void attn_unit(int b,int h,int qb,unsigned char*wsb,char*shm,float kmax,const int CMB,float lam){
;     ...
;   const float mhat=sqrtf(q2_)*kmax*1.004f+0.02f;
;   float l_reg=0.f;f32x16 o[2];o[0]=f32x16{};o[1]=f32x16{};f32x16 o2[2];o2[0]=f32x16{};o2[1]=f32x16{};const f32x16 negm=f32x16{};
;   const int qrel=wid*QBLK+r32;
;     ...
;   bool resc=false;
;     ...
;   f32x16 pA0,pA1,pB0,pB1;
;   int sl_prev=0,sl_cur=0,sl_next=SLOTB;
;     ...
;   DMA_K(2,2*SLOTB);
;   WAIT_BAR(4);
;   qkt(pA0,pA1,Kbase,qr,negm,r32,hi);asm volatile("s_nop 15\n\ts_nop 7":"+v"(pA0),"+v"(pA1));CMASK(pA0,pA1,0);
;   START(pA0,pA1);
;   _Pragma("unroll") for(int r=0;r<16;++r)pA1[r]=__builtin_amdgcn_exp2f(pA1[r]);
;   WAIT_BAR(0);
;   DMA_K(3,0);DMA_V(1,SLOTB);
;   ROT();
;   kload8(kf,kp0+sl_cur);
;   WAIT_BAR(3);
; __global__ void __launch_bounds__(NTHR, 2) fwd_megakernel(Args args_unused) {
;     ...
;                     const float kmax = 1.01f * sqrtf(__uint_as_float(__builtin_amdgcn_readfirstlane(__hip_atomic_load((unsigned*)(ws + WS_KMAX) + 2 * bh, __ATOMIC_RELAXED, __HIP_MEMORY_SCOPE_AGENT)))
;                                                    + __uint_as_float(__builtin_amdgcn_readfirstlane(__hip_atomic_load((unsigned*)(ws + WS_KMAX) + 2 * bh + 1, __ATOMIC_RELAXED, __HIP_MEMORY_SCOPE_AGENT))));
.LBB0_309:
	v_mov_b32_e32 v39, s6
	v_add_f32_e32 v39, s5, v39
	v_mul_f32_e32 v40, 0x4f800000, v39
	v_cmp_gt_f32_e32 vcc, s74, v39
	v_add_f32_e32 v37, v37, v38
	v_mul_f32_e32 v38, 0x4f800000, v37
	v_cndmask_b32_e32 v39, v39, v40, vcc
	v_sqrt_f32_e32 v40, v39
	s_waitcnt vmcnt(0) lgkmcnt(0)
	s_barrier
	s_cmp_lg_u32 0, -1
	s_mov_b32 s37, 0
	v_add_u32_e32 v41, -1, v40
	v_fma_f32 v42, -v41, v40, v39
	v_cmp_ge_f32_e64 s[4:5], 0, v42
	v_add_u32_e32 v42, 1, v40
	s_mov_b32 s6, 1
	v_cndmask_b32_e64 v41, v40, v41, s[4:5]
	v_fma_f32 v40, -v42, v40, v39
	v_cmp_lt_f32_e64 s[4:5], 0, v40
	s_nop 1
	v_cndmask_b32_e64 v40, v41, v42, s[4:5]
	v_mul_f32_e32 v41, 0x37800000, v40
	v_cndmask_b32_e32 v40, v40, v41, vcc
	v_cmp_class_f32_e32 vcc, v39, v237
	s_nop 1
	v_cndmask_b32_e32 v39, v40, v39, vcc
	v_cmp_gt_f32_e32 vcc, s74, v37
	v_lshlrev_b32_e32 v40, 1, v36
	v_and_b32_e32 v251, 32, v40
	v_cndmask_b32_e32 v37, v37, v38, vcc
	v_sqrt_f32_e32 v38, v37
	v_lshlrev_b32_e32 v40, 4, v36
	v_and_b32_e32 v40, 0xc0, v40
	v_lshl_or_b32 v246, v242, 8, v40
	v_add_u32_e32 v40, 0, v251
	v_add3_u32 v252, v40, v249, v246
	v_add_u32_e32 v40, -1, v38
	v_fma_f32 v41, -v40, v38, v37
	v_cmp_ge_f32_e64 s[4:5], 0, v41
	v_add_u32_e32 v41, 1, v38
	v_mul_f32_e32 v39, 0x3f8147ae, v39
	v_cndmask_b32_e64 v40, v38, v40, s[4:5]
	v_fma_f32 v38, -v41, v38, v37
	v_cmp_lt_f32_e64 s[4:5], 0, v38
	s_nop 1
	v_cndmask_b32_e64 v38, v40, v41, s[4:5]
	v_mul_f32_e32 v40, 0x37800000, v38
	v_cndmask_b32_e32 v38, v38, v40, vcc
	v_cmp_class_f32_e32 vcc, v37, v237
	s_mov_b64 s[4:5], 0x60000
	s_nop 0
	v_cndmask_b32_e32 v37, v38, v37, vcc
	v_mul_f32_e32 v37, v39, v37
	v_fmamk_f32 v247, v37, 0x3f808312, v238
	v_sub_f32_e32 v0, v0, v247
	v_sub_f32_e32 v1, v1, v247
	v_sub_f32_e32 v16, v16, v247
	v_sub_f32_e32 v17, v17, v247
	v_sub_f32_e32 v2, v2, v247
	v_sub_f32_e32 v18, v18, v247
	s_nop 0
	v_exp_f32_e32 v96, v0
	v_exp_f32_e32 v97, v1
	v_lshl_add_u64 v[0:1], v[32:33], 0, s[4:5]
	s_mov_b32 s4, m0
	s_mov_b32 m0, s3
	s_nop 0
	global_load_lds_dwordx4 v[0:1], off
	s_mov_b32 m0, s4
	s_mov_b64 s[4:5], 0x20000
	v_lshl_add_u64 v[0:1], v[34:35], 0, s[4:5]
	s_cselect_b32 s4, 0, 0
	s_add_i32 s1, s4, s1
	s_add_i32 s4, s1, 0x8000
	s_mov_b32 s5, m0
	s_mov_b32 m0, s4
	s_nop 0
	global_load_lds_dwordx4 v[0:1], off
	s_mov_b32 m0, s5
	s_mov_b64 s[4:5], 0x20080
	v_lshl_add_u64 v[0:1], v[34:35], 0, s[4:5]
	s_add_i32 s1, s1, 0xe000
	s_mov_b32 s4, m0
	s_mov_b32 m0, s1
	s_nop 0
	global_load_lds_dwordx4 v[0:1], off
	s_mov_b32 m0, s4
	ds_read_b128 v[204:207], v250 offset:8192
	ds_read_b128 v[200:203], v250 offset:8704
	ds_read_b128 v[196:199], v250 offset:10240
	ds_read_b128 v[192:195], v250 offset:10752
	ds_read_b128 v[188:191], v250 offset:12288
	ds_read_b128 v[184:187], v250 offset:12800
	ds_read_b128 v[180:183], v250 offset:14336
	ds_read_b128 v[176:179], v250 offset:14848
	v_sub_f32_e32 v3, v3, v247
	v_sub_f32_e32 v19, v19, v247
	v_sub_f32_e32 v4, v4, v247
	v_sub_f32_e32 v20, v20, v247
	v_sub_f32_e32 v5, v5, v247
	v_sub_f32_e32 v21, v21, v247
	v_sub_f32_e32 v6, v6, v247
	v_sub_f32_e32 v22, v22, v247
	v_sub_f32_e32 v7, v7, v247
	v_sub_f32_e32 v23, v23, v247
	v_sub_f32_e32 v8, v8, v247
	v_sub_f32_e32 v24, v24, v247
	v_sub_f32_e32 v9, v9, v247
	v_sub_f32_e32 v25, v25, v247
	v_sub_f32_e32 v10, v10, v247
	v_sub_f32_e32 v26, v26, v247
	v_sub_f32_e32 v11, v11, v247
	v_sub_f32_e32 v27, v27, v247
	v_sub_f32_e32 v12, v12, v247
	v_sub_f32_e32 v28, v28, v247
	v_sub_f32_e32 v13, v13, v247
	v_sub_f32_e32 v29, v29, v247
	v_sub_f32_e32 v14, v14, v247
	v_sub_f32_e32 v30, v30, v247
	v_sub_f32_e32 v15, v15, v247
	v_sub_f32_e32 v31, v31, v247
	v_exp_f32_e32 v98, v2
	v_exp_f32_e32 v99, v3
	v_exp_f32_e32 v100, v4
	v_exp_f32_e32 v101, v5
	v_exp_f32_e32 v102, v6
	v_exp_f32_e32 v103, v7
	v_exp_f32_e32 v104, v8
	v_exp_f32_e32 v105, v9
	v_exp_f32_e32 v106, v10
	v_exp_f32_e32 v107, v11
	v_exp_f32_e32 v108, v12
	v_exp_f32_e32 v109, v13
	v_exp_f32_e32 v110, v14
	v_exp_f32_e32 v111, v15
	v_exp_f32_e32 v80, v16
	v_exp_f32_e32 v81, v17
	v_exp_f32_e32 v82, v18
	v_exp_f32_e32 v83, v19
	v_exp_f32_e32 v84, v20
	v_exp_f32_e32 v85, v21
	v_exp_f32_e32 v86, v22
	v_exp_f32_e32 v87, v23
	v_exp_f32_e32 v88, v24
	v_exp_f32_e32 v89, v25
	v_exp_f32_e32 v90, v26
	v_exp_f32_e32 v91, v27
	v_exp_f32_e32 v92, v28
	v_exp_f32_e32 v93, v29
	v_exp_f32_e32 v94, v30
	v_exp_f32_e32 v95, v31
	s_waitcnt vmcnt(3) lgkmcnt(0)
	s_barrier
	v_and_b32_e32 v0, 3, v36
	s_andn2_b64 vcc, exec, s[54:55]
	v_lshlrev_b32_e32 v208, 4, v0
	s_cbranch_vccnz .LBB0_313
; template<int THRL> __device__ __forceinline__ void attn_unit(int b,int h,int qb,unsigned char*wsb,char*shm,float kmax,const int CMB,float lam){
;     ...
;   float l_reg=0.f;f32x16 o[2];o[0]=f32x16{};o[1]=f32x16{};f32x16 o2[2];o2[0]=f32x16{};o2[1]=f32x16{};const f32x16 negm=f32x16{};
;   const int qrel=wid*QBLK+r32;
;     ...
;   bool resc=false;
;     ...
;   f32x16 pA0,pA1,pB0,pB1;
;   int sl_prev=0,sl_cur=0,sl_next=SLOTB;
	s_lshl_b32 s1, s43, 6
	s_add_i32 s6, s79, s1
	s_lshr_b32 s4, s6, 7
	s_mov_b32 s5, s7
	s_lshl_b64 s[4:5], s[4:5], 8
	s_lshl_b64 s[36:37], s[68:69], 1
	s_add_u32 s4, s36, s4
	v_mov_b32_e32 v209, v221
	s_addc_u32 s5, s37, s5
	s_lshl_b32 s1, s95, 9
	v_lshl_add_u64 v[0:1], s[4:5], 0, v[208:209]
	s_and_b32 s1, s1, 0x18000
	s_lshl_b64 s[4:5], s[66:67], 1
	s_lshl_b64 s[36:37], s[6:7], 1
	v_lshl_or_b32 v2, v214, 11, s1
	s_add_u32 s1, s64, s36
	s_addc_u32 s6, s65, s37
	v_mov_b32_e32 v3, v221
	s_add_u32 s4, s1, s4
	v_lshl_add_u64 v[0:1], v[0:1], 0, v[2:3]
	s_addc_u32 s5, s6, s5
	v_mov_b32_e32 v64, 0
	s_mov_b32 s33, 6
	v_lshl_add_u64 v[210:211], s[64:65], 0, v[0:1]
	v_lshl_add_u64 v[212:213], s[4:5], 0, v[220:221]
	s_movk_i32 s36, 0x4000
	s_movk_i32 s42, 0x2000
	s_mov_b32 s5, 0
	v_mov_b32_e32 v0, 0
	v_mov_b32_e32 v1, v64
	v_mov_b32_e32 v2, v64
	v_mov_b32_e32 v3, v64
	v_mov_b32_e32 v4, v64
	v_mov_b32_e32 v5, v64
	v_mov_b32_e32 v6, v64
	v_mov_b32_e32 v7, v64
	v_mov_b32_e32 v8, v64
	v_mov_b32_e32 v9, v64
	v_mov_b32_e32 v10, v64
	v_mov_b32_e32 v11, v64
	v_mov_b32_e32 v12, v64
	v_mov_b32_e32 v13, v64
	v_mov_b32_e32 v14, v64
	v_mov_b32_e32 v15, v64
	v_mov_b32_e32 v16, 0
	v_mov_b32_e32 v17, v64
	v_mov_b32_e32 v18, v64
	v_mov_b32_e32 v19, v64
	v_mov_b32_e32 v20, v64
	v_mov_b32_e32 v21, v64
	v_mov_b32_e32 v22, v64
	v_mov_b32_e32 v23, v64
	v_mov_b32_e32 v24, v64
	v_mov_b32_e32 v25, v64
	v_mov_b32_e32 v26, v64
	v_mov_b32_e32 v27, v64
	v_mov_b32_e32 v28, v64
	v_mov_b32_e32 v29, v64
	v_mov_b32_e32 v30, v64
	v_mov_b32_e32 v31, v64
	v_mov_b32_e32 v32, 0
	v_mov_b32_e32 v33, v64
	v_mov_b32_e32 v34, v64
	v_mov_b32_e32 v35, v64
	v_mov_b32_e32 v36, v64
	v_mov_b32_e32 v37, v64
	v_mov_b32_e32 v38, v64
	v_mov_b32_e32 v39, v64
	v_mov_b32_e32 v40, v64
	v_mov_b32_e32 v41, v64
	v_mov_b32_e32 v42, v64
	v_mov_b32_e32 v43, v64
	v_mov_b32_e32 v44, v64
	v_mov_b32_e32 v45, v64
	v_mov_b32_e32 v46, v64
	v_mov_b32_e32 v47, v64
	v_mov_b32_e32 v48, 0
	v_mov_b32_e32 v49, v64
	v_mov_b32_e32 v50, v64
	v_mov_b32_e32 v51, v64
	v_mov_b32_e32 v52, v64
	v_mov_b32_e32 v53, v64
	v_mov_b32_e32 v54, v64
	v_mov_b32_e32 v55, v64
	v_mov_b32_e32 v56, v64
	v_mov_b32_e32 v57, v64
	v_mov_b32_e32 v58, v64
	v_mov_b32_e32 v59, v64
	v_mov_b32_e32 v60, v64
	v_mov_b32_e32 v61, v64
	v_mov_b32_e32 v62, v64
	v_mov_b32_e32 v63, v64
	v_lshlrev_b32_e32 v143, 2, v230
	v_add_u32_e32 v143, 0x12800, v143
	ds_write_b32 v143, v246 offset:32768
	ds_write_b32 v143, v230
	ds_write_b32 v143, v231 offset:2048
	ds_write_b32 v143, v232 offset:4096
	ds_write_b32 v143, v233 offset:6144
	ds_write_b32 v143, v234 offset:8192
	ds_write_b32 v143, v235 offset:10240
	ds_write_b32 v143, v236 offset:12288
	ds_write_b32 v143, v237 offset:14336
	ds_write_b32 v143, v238 offset:16384
	ds_write_b32 v143, v239 offset:18432
	ds_write_b32 v143, v240 offset:20480
	ds_write_b32 v143, v241 offset:22528
	ds_write_b32 v143, v242 offset:24576
	ds_write_b32 v143, v243 offset:26624
	ds_write_b32 v143, v244 offset:28672
	ds_write_b32 v143, v245 offset:30720
	v_mov_b32_e32 v246, v143
	v_xor_b32_e32 v230, 0x80000000, v247
	v_mov_b32_e32 v231, v230
	v_mov_b32_e32 v232, v230
	v_mov_b32_e32 v233, v230
	v_mov_b32_e32 v234, v230
	v_mov_b32_e32 v235, v230
	v_mov_b32_e32 v236, v230
	v_mov_b32_e32 v237, v230
	v_mov_b32_e32 v238, v230
	v_mov_b32_e32 v239, v230
	v_mov_b32_e32 v240, v230
	v_mov_b32_e32 v241, v230
	v_mov_b32_e32 v242, v230
	v_mov_b32_e32 v243, v230
	v_mov_b32_e32 v244, v230
	v_mov_b32_e32 v245, v230
	s_waitcnt lgkmcnt(0)
.LBB0_311:
	s_mov_b32 s37, s36
	s_mov_b32 s4, s33
	s_mov_b32 s1, s42
	v_add_u32_e32 v209, s5, v252
	ds_read_b64_tr_b16 v[216:217], v209 offset:24576
	ds_read_b64_tr_b16 v[218:219], v209 offset:25088
	v_add_f32_e32 v65, v96, v97
	v_add_f32_e32 v65, v98, v65
	v_add_f32_e32 v65, v99, v65
	v_add_f32_e32 v65, v100, v65
	v_add_f32_e32 v65, v101, v65
	v_cvt_pk_bf16_f32 v172, v96, v97
	v_cvt_pk_bf16_f32 v173, v98, v99
	s_waitcnt lgkmcnt(9)
	v_mfma_f32_32x32x16_bf16 v[128:143], v[204:207], v[156:159], v[230:245]
	ds_read_b64_tr_b16 v[204:205], v209 offset:28672
	ds_read_b64_tr_b16 v[206:207], v209 offset:29184
	v_add_f32_e32 v65, v102, v65
	v_add_f32_e32 v65, v103, v65
	v_add_f32_e32 v65, v104, v65
	v_add_f32_e32 v65, v105, v65
	v_cvt_pk_bf16_f32 v174, v100, v101
	v_cvt_pk_bf16_f32 v175, v102, v103
	s_waitcnt lgkmcnt(10)
	v_mfma_f32_32x32x16_bf16 v[112:127], v[200:203], v[156:159], v[230:245]
	ds_read_b64_tr_b16 v[74:75], v209 offset:25600
	ds_read_b64_tr_b16 v[76:77], v209 offset:26112
	v_add_f32_e32 v65, v106, v65
	v_add_f32_e32 v65, v107, v65
	v_add_f32_e32 v65, v108, v65
	v_add_f32_e32 v65, v109, v65
	v_cvt_pk_bf16_f32 v168, v104, v105
	v_cvt_pk_bf16_f32 v169, v106, v107
	s_waitcnt lgkmcnt(11)
	v_mfma_f32_32x32x16_bf16 v[128:143], v[196:199], v[152:155], v[128:143]
	ds_read_b64_tr_b16 v[70:71], v209 offset:29696
	ds_read_b64_tr_b16 v[72:73], v209 offset:30208
	v_add_f32_e32 v65, v110, v65
	v_add_f32_e32 v65, v111, v65
	v_add_f32_e32 v65, v80, v65
	v_add_f32_e32 v65, v81, v65
	v_cvt_pk_bf16_f32 v170, v108, v109
	v_cvt_pk_bf16_f32 v171, v110, v111
	s_waitcnt lgkmcnt(12)
	v_mfma_f32_32x32x16_bf16 v[112:127], v[192:195], v[152:155], v[112:127]
	ds_read_b64_tr_b16 v[66:67], v209 offset:26624
	ds_read_b64_tr_b16 v[68:69], v209 offset:27136
	v_add_f32_e32 v65, v82, v65
	v_add_f32_e32 v65, v83, v65
	v_add_f32_e32 v65, v84, v65
	v_add_f32_e32 v65, v85, v65
	v_cvt_pk_bf16_f32 v164, v80, v81
	v_cvt_pk_bf16_f32 v165, v82, v83
	s_waitcnt lgkmcnt(13)
	v_mfma_f32_32x32x16_bf16 v[128:143], v[188:191], v[148:151], v[128:143]
	ds_read_b64_tr_b16 v[100:101], v209 offset:30720
	ds_read_b64_tr_b16 v[102:103], v209 offset:31232
	v_add_f32_e32 v65, v86, v65
	v_add_f32_e32 v65, v87, v65
	v_add_f32_e32 v65, v88, v65
	v_add_f32_e32 v65, v89, v65
	v_cvt_pk_bf16_f32 v166, v84, v85
	v_cvt_pk_bf16_f32 v167, v86, v87
	s_waitcnt lgkmcnt(14)
	v_mfma_f32_32x32x16_bf16 v[112:127], v[184:187], v[148:151], v[112:127]
	ds_read_b64_tr_b16 v[96:97], v209 offset:27648
	ds_read_b64_tr_b16 v[98:99], v209 offset:28160
	v_add_f32_e32 v65, v90, v65
	v_add_f32_e32 v65, v91, v65
	v_add_f32_e32 v65, v92, v65
	v_add_f32_e32 v65, v93, v65
	v_cvt_pk_bf16_f32 v160, v88, v89
	v_cvt_pk_bf16_f32 v161, v90, v91
	s_waitcnt lgkmcnt(14)
	v_mfma_f32_32x32x16_bf16 v[128:143], v[180:183], v[144:147], v[128:143]
	ds_read_b64_tr_b16 v[86:87], v209 offset:31744
	ds_read_b64_tr_b16 v[88:89], v209 offset:32256
	v_add_f32_e32 v65, v94, v65
	v_add_f32_e32 v65, v95, v65
	v_add_f32_e32 v65, 0, v65
	v_cvt_pk_bf16_f32 v162, v92, v93
	v_cvt_pk_bf16_f32 v163, v94, v95
	v_mfma_f32_32x32x16_bf16 v[112:127], v[176:179], v[144:147], v[112:127]
	v_lshl_add_u64 v[190:191], v[212:213], 0, s[48:49]
	v_lshl_add_u64 v[78:79], v[190:191], 0, s[10:11]
	s_add_i32 s5, s42, s3
	s_mov_b32 s6, m0
	s_mov_b32 m0, s5
	s_nop 0
	global_load_lds_dwordx4 v[78:79], off
	s_mov_b32 m0, s6
	v_lshl_add_u64 v[188:189], v[210:211], 0, s[48:49]
	v_lshl_add_u64 v[78:79], v[188:189], 0, s[12:13]
	s_add_i32 s5, s36, s97
	s_mov_b32 s6, m0
	s_mov_b32 m0, s5
	s_nop 0
	global_load_lds_dwordx4 v[78:79], off
	s_mov_b32 m0, s6
	v_lshl_add_u64 v[78:79], v[188:189], 0, s[14:15]
	s_add_i32 s5, s36, s96
	s_mov_b32 s6, m0
	s_mov_b32 m0, s5
	s_nop 0
	global_load_lds_dwordx4 v[78:79], off
	s_mov_b32 m0, s6
	s_waitcnt lgkmcnt(14)
	v_mfma_f32_32x32x16_bf16 v[32:47], v[172:175], v[216:219], v[32:47]
	v_exp_f32_e32 v128, v128
	v_exp_f32_e32 v129, v129
	ds_read_b64_tr_b16 v[90:91], v209 offset:49152
	ds_read_b64_tr_b16 v[92:93], v209 offset:49664
	s_waitcnt lgkmcnt(14)
	v_mfma_f32_32x32x16_bf16 v[48:63], v[172:175], v[204:207], v[48:63]
	v_exp_f32_e32 v130, v130
	v_exp_f32_e32 v131, v131
	ds_read_b64_tr_b16 v[104:105], v209 offset:53248
	ds_read_b64_tr_b16 v[106:107], v209 offset:53760
	v_add_u32_e32 v94, s37, v250
	ds_read_b128 v[82:85], v94
	ds_read_b128 v[78:81], v94 offset:512
	s_waitcnt lgkmcnt(14)
	v_mfma_f32_32x32x16_bf16 v[32:47], v[168:171], v[74:77], v[32:47]
	v_exp_f32_e32 v132, v132
	v_exp_f32_e32 v133, v133
	ds_read_b64_tr_b16 v[108:109], v209 offset:50176
	ds_read_b64_tr_b16 v[110:111], v209 offset:50688
	ds_read_b128 v[184:187], v94 offset:2048
	ds_read_b128 v[176:179], v94 offset:2560
	v_mfma_f32_32x32x16_bf16 v[48:63], v[168:171], v[70:73], v[48:63]
	v_exp_f32_e32 v134, v134
	v_exp_f32_e32 v135, v135
	ds_read_b64_tr_b16 v[192:193], v209 offset:54272
	ds_read_b64_tr_b16 v[194:195], v209 offset:54784
	ds_read_b128 v[180:183], v94 offset:4096
	ds_read_b128 v[70:73], v94 offset:4608
	s_waitcnt lgkmcnt(14)
	v_mfma_f32_32x32x16_bf16 v[32:47], v[164:167], v[66:69], v[32:47]
	v_exp_f32_e32 v136, v136
	v_exp_f32_e32 v137, v137
	ds_read_b64_tr_b16 v[196:197], v209 offset:51200
	ds_read_b64_tr_b16 v[198:199], v209 offset:51712
	ds_read_b128 v[74:77], v94 offset:6144
	ds_read_b128 v[66:69], v94 offset:6656
	v_mfma_f32_32x32x16_bf16 v[48:63], v[164:167], v[100:103], v[48:63]
	v_exp_f32_e32 v138, v138
	v_exp_f32_e32 v139, v139
	ds_read_b64_tr_b16 v[100:101], v209 offset:55296
	ds_read_b64_tr_b16 v[102:103], v209 offset:55808
	v_mfma_f32_32x32x16_bf16 v[32:47], v[160:163], v[96:99], v[32:47]
	v_exp_f32_e32 v140, v140
	v_exp_f32_e32 v141, v141
	ds_read_b64_tr_b16 v[94:95], v209 offset:52224
	ds_read_b64_tr_b16 v[96:97], v209 offset:52736
	v_mfma_f32_32x32x16_bf16 v[48:63], v[160:163], v[86:89], v[48:63]
	v_exp_f32_e32 v142, v142
	v_exp_f32_e32 v143, v143
	ds_read_b64_tr_b16 v[86:87], v209 offset:56320
	ds_read_b64_tr_b16 v[88:89], v209 offset:56832
	s_waitcnt lgkmcnt(14)
	v_mfma_f32_32x32x16_bf16 v[0:15], v[172:175], v[90:93], v[0:15]
	v_exp_f32_e32 v112, v112
	v_exp_f32_e32 v113, v113
	v_mfma_f32_32x32x16_bf16 v[16:31], v[172:175], v[104:107], v[16:31]
	v_exp_f32_e32 v114, v114
	v_exp_f32_e32 v115, v115
	v_mfma_f32_32x32x16_bf16 v[0:15], v[168:171], v[108:111], v[0:15]
	v_exp_f32_e32 v116, v116
	v_exp_f32_e32 v117, v117
	s_waitcnt lgkmcnt(12)
	v_mfma_f32_32x32x16_bf16 v[16:31], v[168:171], v[192:195], v[16:31]
	v_exp_f32_e32 v118, v118
	v_exp_f32_e32 v119, v119
	s_waitcnt lgkmcnt(8)
	v_mfma_f32_32x32x16_bf16 v[0:15], v[164:167], v[196:199], v[0:15]
	v_exp_f32_e32 v120, v120
	v_exp_f32_e32 v121, v121
	s_waitcnt lgkmcnt(4)
	v_mfma_f32_32x32x16_bf16 v[16:31], v[164:167], v[100:103], v[16:31]
	v_exp_f32_e32 v122, v122
	v_exp_f32_e32 v123, v123
	s_waitcnt lgkmcnt(2)
	v_mfma_f32_32x32x16_bf16 v[0:15], v[160:163], v[94:97], v[0:15]
	v_exp_f32_e32 v124, v124
	v_exp_f32_e32 v125, v125
	s_waitcnt lgkmcnt(0)
	v_mfma_f32_32x32x16_bf16 v[16:31], v[160:163], v[86:89], v[16:31]
	v_exp_f32_e32 v126, v126
	v_exp_f32_e32 v127, v127
	s_waitcnt vmcnt(3) lgkmcnt(0)
	s_barrier
	s_add_i32 s5, s36, 0x2000
	s_cmpk_lg_i32 s36, 0x4000
	s_cselect_b32 s42, s5, 0
	v_add_u32_e32 v209, s1, v252
	ds_read_b64_tr_b16 v[192:193], v209 offset:24576
	ds_read_b64_tr_b16 v[194:195], v209 offset:25088
	v_mfma_f32_32x32x16_bf16 v[96:111], v[82:85], v[156:159], v[230:245]
	v_add_f32_e32 v86, v128, v129
	v_add_f32_e32 v86, v130, v86
	v_add_f32_e32 v86, v131, v86
	v_add_f32_e32 v86, v132, v86
	v_add_f32_e32 v86, v133, v86
	v_cvt_pk_bf16_f32 v172, v128, v129
	v_cvt_pk_bf16_f32 v173, v130, v131
	ds_read_b64_tr_b16 v[196:197], v209 offset:28672
	ds_read_b64_tr_b16 v[198:199], v209 offset:29184
	v_add_f32_e32 v82, v134, v86
	v_add_f32_e32 v82, v135, v82
	v_add_f32_e32 v82, v136, v82
	v_add_f32_e32 v128, v137, v82
	v_mfma_f32_32x32x16_bf16 v[80:95], v[78:81], v[156:159], v[230:245]
	v_cvt_pk_bf16_f32 v174, v132, v133
	v_cvt_pk_bf16_f32 v175, v134, v135
	ds_read_b64_tr_b16 v[216:217], v209 offset:25600
	ds_read_b64_tr_b16 v[218:219], v209 offset:26112
	v_mfma_f32_32x32x16_bf16 v[96:111], v[184:187], v[152:155], v[96:111]
	v_add_f32_e32 v78, v138, v128
	v_add_f32_e32 v78, v139, v78
	v_add_f32_e32 v78, v140, v78
	v_add_f32_e32 v78, v141, v78
	v_cvt_pk_bf16_f32 v168, v136, v137
	v_cvt_pk_bf16_f32 v169, v138, v139
	ds_read_b64_tr_b16 v[136:137], v209 offset:29696
	ds_read_b64_tr_b16 v[138:139], v209 offset:30208
	v_mfma_f32_32x32x16_bf16 v[80:95], v[176:179], v[152:155], v[80:95]
	v_add_f32_e32 v78, v142, v78
	v_add_f32_e32 v78, v143, v78
	v_add_f32_e32 v78, v112, v78
	v_add_f32_e32 v78, v113, v78
	v_cvt_pk_bf16_f32 v170, v140, v141
	v_cvt_pk_bf16_f32 v171, v142, v143
	ds_read_b64_tr_b16 v[132:133], v209 offset:26624
	ds_read_b64_tr_b16 v[134:135], v209 offset:27136
	v_mfma_f32_32x32x16_bf16 v[96:111], v[180:183], v[148:151], v[96:111]
	v_add_f32_e32 v78, v114, v78
	v_add_f32_e32 v78, v115, v78
	v_add_f32_e32 v78, v116, v78
	v_add_f32_e32 v78, v117, v78
	v_cvt_pk_bf16_f32 v164, v112, v113
	v_cvt_pk_bf16_f32 v165, v114, v115
	ds_read_b64_tr_b16 v[128:129], v209 offset:30720
	ds_read_b64_tr_b16 v[130:131], v209 offset:31232
	v_mfma_f32_32x32x16_bf16 v[80:95], v[70:73], v[148:151], v[80:95]
	v_add_f32_e32 v78, v118, v78
	v_add_f32_e32 v78, v119, v78
	v_add_f32_e32 v78, v120, v78
	v_add_f32_e32 v78, v121, v78
	v_cvt_pk_bf16_f32 v166, v116, v117
	v_cvt_pk_bf16_f32 v167, v118, v119
	ds_read_b64_tr_b16 v[112:113], v209 offset:27648
	ds_read_b64_tr_b16 v[114:115], v209 offset:28160
	v_mfma_f32_32x32x16_bf16 v[96:111], v[74:77], v[144:147], v[96:111]
	v_add_f32_e32 v70, v122, v78
	v_add_f32_e32 v70, v123, v70
	v_add_f32_e32 v70, v124, v70
	v_add_f32_e32 v78, v125, v70
	v_cvt_pk_bf16_f32 v160, v120, v121
	v_cvt_pk_bf16_f32 v161, v122, v123
	ds_read_b64_tr_b16 v[70:71], v209 offset:31744
	ds_read_b64_tr_b16 v[72:73], v209 offset:32256
	v_mfma_f32_32x32x16_bf16 v[80:95], v[66:69], v[144:147], v[80:95]
	v_add_f32_e32 v74, v126, v78
	v_add_f32_e32 v74, v127, v74
	v_add_f32_e32 v74, 0, v74
	v_cvt_pk_bf16_f32 v162, v124, v125
	v_cvt_pk_bf16_f32 v163, v126, v127
	v_lshl_add_u64 v[66:67], v[190:191], 0, s[16:17]
	s_add_i32 s1, s36, s3
	s_mov_b32 s5, m0
	s_mov_b32 m0, s1
	s_nop 0
	global_load_lds_dwordx4 v[66:67], off
	s_mov_b32 m0, s5
	v_lshl_add_u64 v[66:67], v[188:189], 0, s[18:19]
	s_add_i32 s1, s42, s97
	s_mov_b32 s5, m0
	s_mov_b32 m0, s1
	s_nop 0
	global_load_lds_dwordx4 v[66:67], off
	s_mov_b32 m0, s5
	v_lshl_add_u64 v[66:67], v[188:189], 0, s[20:21]
	s_add_i32 s1, s42, s96
	s_mov_b32 s5, m0
	s_mov_b32 m0, s1
	s_nop 0
	global_load_lds_dwordx4 v[66:67], off
	s_mov_b32 m0, s5
	s_waitcnt lgkmcnt(14)
	v_mfma_f32_32x32x16_bf16 v[32:47], v[172:175], v[192:195], v[32:47]
	v_exp_f32_e32 v96, v96
	v_exp_f32_e32 v97, v97
	ds_read_b64_tr_b16 v[66:67], v209 offset:49152
	ds_read_b64_tr_b16 v[68:69], v209 offset:49664
	s_waitcnt lgkmcnt(14)
	v_mfma_f32_32x32x16_bf16 v[48:63], v[172:175], v[196:199], v[48:63]
	v_exp_f32_e32 v98, v98
	v_exp_f32_e32 v99, v99
	ds_read_b64_tr_b16 v[76:77], v209 offset:53248
	ds_read_b64_tr_b16 v[78:79], v209 offset:53760
	v_add_u32_e32 v75, s42, v250
	ds_read_b128 v[204:207], v75
	ds_read_b128 v[200:203], v75 offset:512
	s_waitcnt lgkmcnt(14)
	v_mfma_f32_32x32x16_bf16 v[32:47], v[168:171], v[216:219], v[32:47]
	v_exp_f32_e32 v100, v100
	v_exp_f32_e32 v101, v101
	ds_read_b64_tr_b16 v[116:117], v209 offset:50176
	ds_read_b64_tr_b16 v[118:119], v209 offset:50688
	ds_read_b128 v[196:199], v75 offset:2048
	ds_read_b128 v[192:195], v75 offset:2560
	v_mfma_f32_32x32x16_bf16 v[48:63], v[168:171], v[136:139], v[48:63]
	v_exp_f32_e32 v102, v102
	v_exp_f32_e32 v103, v103
	ds_read_b64_tr_b16 v[120:121], v209 offset:54272
	ds_read_b64_tr_b16 v[122:123], v209 offset:54784
	ds_read_b128 v[188:191], v75 offset:4096
	ds_read_b128 v[184:187], v75 offset:4608
	s_waitcnt lgkmcnt(14)
	v_mfma_f32_32x32x16_bf16 v[32:47], v[164:167], v[132:135], v[32:47]
	v_exp_f32_e32 v104, v104
	v_exp_f32_e32 v105, v105
	ds_read_b64_tr_b16 v[124:125], v209 offset:51200
	ds_read_b64_tr_b16 v[126:127], v209 offset:51712
	ds_read_b128 v[180:183], v75 offset:6144
	ds_read_b128 v[176:179], v75 offset:6656
	v_mfma_f32_32x32x16_bf16 v[48:63], v[164:167], v[128:131], v[48:63]
	v_exp_f32_e32 v106, v106
	v_exp_f32_e32 v107, v107
	ds_read_b64_tr_b16 v[128:129], v209 offset:55296
	ds_read_b64_tr_b16 v[130:131], v209 offset:55808
	v_mfma_f32_32x32x16_bf16 v[32:47], v[160:163], v[112:115], v[32:47]
	v_exp_f32_e32 v108, v108
	v_exp_f32_e32 v109, v109
	ds_read_b64_tr_b16 v[112:113], v209 offset:52224
	ds_read_b64_tr_b16 v[114:115], v209 offset:52736
	v_mfma_f32_32x32x16_bf16 v[48:63], v[160:163], v[70:73], v[48:63]
	v_exp_f32_e32 v110, v110
	v_exp_f32_e32 v111, v111
	ds_read_b64_tr_b16 v[70:71], v209 offset:56320
	ds_read_b64_tr_b16 v[72:73], v209 offset:56832
	s_waitcnt lgkmcnt(14)
	v_mfma_f32_32x32x16_bf16 v[0:15], v[172:175], v[66:69], v[0:15]
	v_exp_f32_e32 v80, v80
	v_exp_f32_e32 v81, v81
	v_mfma_f32_32x32x16_bf16 v[16:31], v[172:175], v[76:79], v[16:31]
	v_exp_f32_e32 v82, v82
	v_exp_f32_e32 v83, v83
	v_mfma_f32_32x32x16_bf16 v[0:15], v[168:171], v[116:119], v[0:15]
	v_exp_f32_e32 v84, v84
	v_exp_f32_e32 v85, v85
	s_waitcnt lgkmcnt(12)
	v_mfma_f32_32x32x16_bf16 v[16:31], v[168:171], v[120:123], v[16:31]
	v_exp_f32_e32 v86, v86
	v_exp_f32_e32 v87, v87
	s_waitcnt lgkmcnt(8)
	v_mfma_f32_32x32x16_bf16 v[0:15], v[164:167], v[124:127], v[0:15]
	v_exp_f32_e32 v88, v88
	v_exp_f32_e32 v89, v89
	s_waitcnt lgkmcnt(4)
	v_mfma_f32_32x32x16_bf16 v[16:31], v[164:167], v[128:131], v[16:31]
	v_exp_f32_e32 v90, v90
	v_exp_f32_e32 v91, v91
	s_waitcnt lgkmcnt(2)
	v_mfma_f32_32x32x16_bf16 v[0:15], v[160:163], v[112:115], v[0:15]
	v_exp_f32_e32 v92, v92
	v_exp_f32_e32 v93, v93
	s_waitcnt lgkmcnt(0)
	v_mfma_f32_32x32x16_bf16 v[16:31], v[160:163], v[70:73], v[16:31]
	v_exp_f32_e32 v94, v94
	v_exp_f32_e32 v95, v95
	s_add_i32 s1, s42, 0x2000
	s_waitcnt vmcnt(3) lgkmcnt(0)
	s_barrier
; #define WAIT_BAR(N) asm volatile("s_waitcnt vmcnt(" #N ") lgkmcnt(0)\n\ts_barrier":::"memory")
;   #define RESC() do{ if(resc){ asm volatile("s_waitcnt lgkmcnt(0)":::"memory"); \
;       _Pragma("unroll") for(int d_=0;d_<2;++d_) _Pragma("unroll") for(int r=0;r<16;++r){const float f_=wsf[crow(r,hi)];o[d_][r]*=f_;o2[d_][r]*=f_;} } }while(0)
;   #define ROT() do{sl_prev=sl_cur;sl_cur=sl_next;sl_next=(sl_next==(NSLOT-1)*SLOTB)?0:sl_next+SLOTB;}while(0)
; template<int THRL> __device__ __forceinline__ void attn_unit(int b,int h,int qb,unsigned char*wsb,char*shm,float kmax,const int CMB,float lam){
;     ...
;   for(;t+5<NT;t+=2){
;     STEP(pB0,pB1,pA0,pA1,t,true,true,true);     WAIT_BAR(3); RESC(); ROT();
;     STEP(pA0,pA1,pB0,pB1,t+1,true,true,true);   WAIT_BAR(3); RESC(); ROT();
;   }
	s_cmpk_lg_i32 s42, 0x4000
	v_add_f32_e32 v64, v64, v65
	s_mov_b32 s5, s36
	s_cselect_b32 s36, s1, 0
	s_add_i32 s33, s33, 2
	v_lshl_add_u64 v[210:211], v[210:211], 0, s[22:23]
	v_lshl_add_u64 v[212:213], v[212:213], 0, s[22:23]
	s_cmp_ge_u32 s33, s89
	v_add_f32_e32 v64, v64, v74
	s_cbranch_scc0 .LBB0_311
	ds_read_b32 v230, v246
	ds_read_b32 v231, v246 offset:2048
	ds_read_b32 v232, v246 offset:4096
	ds_read_b32 v233, v246 offset:6144
	ds_read_b32 v234, v246 offset:8192
	ds_read_b32 v235, v246 offset:10240
	ds_read_b32 v236, v246 offset:12288
	ds_read_b32 v237, v246 offset:14336
	ds_read_b32 v238, v246 offset:16384
	ds_read_b32 v239, v246 offset:18432
	ds_read_b32 v240, v246 offset:20480
	ds_read_b32 v241, v246 offset:22528
	ds_read_b32 v242, v246 offset:24576
	ds_read_b32 v243, v246 offset:26624
	ds_read_b32 v244, v246 offset:28672
	ds_read_b32 v245, v246 offset:30720
	ds_read_b32 v246, v246 offset:32768
	s_waitcnt lgkmcnt(0)
	s_add_i32 s6, s4, -3
	s_branch .LBB0_314
